# 9th padded column tile dropped from in-proj GEMM (5 rounds instead of 6); its 32 real columns computed by a small MFMA block at the start of the prep phase
# speedup vs baseline: 1.0028x; 1.0028x over previous
; #define PG8_BAR __builtin_amdgcn_s_barrier()
;     __host__ __device__ bool next(int i, Unit& u) const {
;         const long L = (long)i * G + c; if (L >= nwg) return false;
;         int wgid = (int)L; { const int q = nwg / NXCD, r = nwg % NXCD, xcd = wgid % NXCD, off = wgid / NXCD; wgid = (xcd < r ? xcd * (q + 1) : r * (q + 1) + (xcd - r) * q) + off; }
; template <class Epi, class Sched>
; __device__ __forceinline__ void gemm_phase(PG8_LAS unsigned char* lds, const Gemm g, const Sched& S, const Epi& E) {
;     const int tid = otid(), wid = __builtin_amdgcn_readfirstlane(tid >> 6), lane = tid & 63, wr = wid >> 2, wc = wid & 3, fr = lane & 15, fq = lane >> 4;
;     const int K = g.K, nt = K / BK;
;     unsigned voffA[2], voffB[2];
; #pragma unroll
;     for (int i = 0; i < 2; ++i) { int R, C; stage_rc(tid * 16 + i * 8192, R, C); const int Rb = Epi::PERM ? ((R & ~31) + perm32(R & 31)) : R;
;         voffA[i] = (unsigned)(R * K + C) * 2u; voffB[i] = (unsigned)(Rb * K + C) * 2u; }
;     const size_t kstep = (size_t)(BK * 2);
;     const size_t hstep = (size_t)HALF * K * 2;
;     const size_t tstep = 2 * hstep;
;     const unsigned ldsw = (unsigned)wid * 1024u;
;     const int foff = lds_byte(fr, fq * 8); const int ua = wr * 8192, ub = wc * 4096;
;     ...
;     Unit cur, nxt; int ui = 0;
;     if (!S.next(0, cur)) return;
;     f32x4 acc[2][2][4][2];
; #pragma unroll
;     for (int a = 0; a < 2; ++a)
; #pragma unroll
;         for (int b = 0; b < 2; ++b)
; #pragma unroll
;             for (int m = 0; m < 4; ++m)
; #pragma unroll
;                 for (int n = 0; n < 2; ++n) acc[a][b][m][n] = (f32x4){0.f, 0.f, 0.f, 0.f};
;     bf16x8 At[4][2], B0[2][2], B1[2][2];
;     int cnt = nt;
;     size_t ck = 0;
;     if constexpr (Sched::SPLIT) { int k0_, kn_; S.krange(cur, nt, k0_, kn_); cnt = kn_; ck = (size_t)k0_ * kstep; }
;     const char* cA = (const char*)g.A + (size_t)cur.pm * tstep + ck; const char* cB = (const char*)g.Bt + (size_t)cur.pn * tstep + ck;
;     S.a_ready(cur);
;     PG8_STAGE(PG8_SB(0, 0), cB, voffB); PG8_STAGE(PG8_SA(0, 0), cA, voffA); PG8_STAGE(PG8_SB(0, 1), cB + hstep, voffB); PG8_STAGE(PG8_SA(0, 1), cA + hstep, voffA);
;     if (wr == 1) PG8_BAR;
;     PG8_WAIT_V(4); PG8_BAR;
;     PG8_STAGE(PG8_SB(1, 0), cB + kstep, voffB); PG8_STAGE(PG8_SA(1, 0), cA + kstep, voffA); PG8_STAGE(PG8_SB(1, 1), cB + hstep + kstep, voffB);
;     PG8_WAIT_V(6); PG8_BAR;
.LBB0_471:
	s_or_b64 exec, exec, s[2:3]
	s_mov_b32 s6, s63
	s_waitcnt lgkmcnt(0)
	v_mov_b32_e32 v1, v253
	s_barrier
	s_cmpk_gt_i32 s6, 0x47f
	v_readfirstlane_b32 s7, v1
	s_cbranch_scc1 .LBB0_483
	v_lshlrev_b32_e32 v5, 4, v1
	v_add_u32_e32 v3, 0x2000, v5
	v_ashrrev_i32_e32 v2, 31, v3
	v_lshrrev_b32_e32 v2, 22, v2
	v_add_u32_e32 v2, v3, v2
	v_ashrrev_i32_e32 v2, 10, v2
	v_mul_i32_i24_e32 v4, 0x400, v2
	v_sub_u32_e32 v3, v3, v4
	v_lshrrev_b32_e32 v4, 4, v3
	v_bitop3_b32 v4, v4, v3, 32 bitop3:0x6c
	v_ashrrev_i32_e32 v3, 31, v4
	v_lshrrev_b32_e32 v3, 26, v3
	v_readlane_b32 s8, v255, 45
	v_add_u32_e32 v6, v4, v3
	v_lshlrev_b32_e32 v7, 3, v2
	s_mul_i32 s3, s8, 0x480000
	v_readlane_b32 s5, v255, 7
	v_ashrrev_i32_e32 v3, 6, v6
	v_and_b32_e32 v7, -16, v7
	v_readlane_b32 s9, v255, 46
	s_mul_hi_u32 s2, s8, 0x480000
	s_add_u32 s8, s5, s3
	v_readlane_b32 s3, v255, 8
	v_add_u32_e32 v7, v3, v7
	s_addc_u32 s9, s3, s2
	v_and_b32_e32 v8, 3, v3
	s_mov_b32 s2, 0x1fffe0
	v_lshrrev_b32_e32 v9, 2, v7
	v_lshlrev_b32_e32 v10, 1, v7
	v_and_b32_e32 v6, 0xc0, v6
	v_and_or_b32 v8, v7, s2, v8
	v_and_b32_e32 v9, 4, v9
	v_and_b32_e32 v10, 24, v10
	v_sub_u32_e32 v4, v4, v6
	v_mov_b32_e32 v12, 1
	v_or3_b32 v8, v8, v9, v10
	v_lshlrev_b32_e32 v9, 5, v2
	v_ashrrev_i16_sdwa v4, v12, sext(v4) dst_sel:DWORD dst_unused:UNUSED_PAD src0_sel:DWORD src1_sel:BYTE_0
	v_and_b32_e32 v9, 32, v9
	v_bfe_i32 v4, v4, 0, 16
	v_add_lshl_u32 v6, v9, v4, 1
	v_lshl_add_u32 v130, v8, 11, v6
	v_lshl_add_u32 v132, v7, 11, v6
	v_bfe_i32 v6, v1, 27, 1
	v_lshrrev_b32_e32 v6, 22, v6
	v_add_u32_e32 v6, v5, v6
	v_and_b32_e32 v6, 0xfffffc00, v6
	v_sub_u32_e32 v5, v5, v6
	v_lshrrev_b32_e32 v6, 4, v5
	v_bitop3_b32 v7, v6, v5, 32 bitop3:0x6c
	v_ashrrev_i32_e32 v6, 31, v1
	v_lshrrev_b32_e32 v6, 26, v6
	v_ashrrev_i32_e32 v5, 31, v5
	v_add_u32_e32 v6, v1, v6
	v_lshrrev_b32_e32 v5, 26, v5
	v_ashrrev_i32_e32 v6, 6, v6
	v_add_u32_e32 v5, v7, v5
	v_lshlrev_b32_e32 v8, 3, v6
	v_ashrrev_i32_e32 v5, 6, v5
	v_and_b32_e32 v8, -16, v8
	v_add_u32_e32 v8, v5, v8
	v_and_b32_e32 v9, 3, v5
	s_ashr_i32 s11, s6, 31
	v_and_or_b32 v9, v8, s2, v9
	s_lshr_b32 s2, s11, 29
	s_add_i32 s2, s6, s2
	s_ashr_i32 s20, s7, 6
	s_ashr_i32 s3, s2, 3
	s_and_b32 s2, s2, -8
	s_ashr_i32 s17, s7, 8
	s_lshl_b32 s10, s20, 10
	s_sub_i32 s2, s6, s2
	s_cmp_lt_i32 s2, 0
	s_movk_i32 s5, 0x91
	s_cselect_b32 s5, s5, 0x90
	s_mul_i32 s2, s2, s5
	s_add_i32 s2, s2, s3
	s_ashr_i32 s3, s2, 6
	s_nop 0
	s_nop 0
	s_nop 0
	s_lshl_b32 s5, s3, 3
	s_mulk_i32 s3, 0x40
	s_sub_i32 s2, s2, s3
	s_bfe_i32 s3, s2, 0x80000
	s_bfe_u32 s3, s3, 0x3000c
	s_add_i32 s3, s2, s3
	s_bfe_i32 s12, s3, 0x80000
	s_and_b32 s3, s3, 0xf8
	v_lshrrev_b32_e32 v10, 2, v8
	v_lshlrev_b32_e32 v11, 1, v8
	s_sub_i32 s2, s2, s3
	v_and_b32_e32 v10, 4, v10
	v_and_b32_e32 v11, 24, v11
	s_sext_i32_i16 s12, s12
	s_sext_i32_i8 s2, s2
	v_or3_b32 v9, v9, v10, v11
	v_mul_i32_i24_e32 v11, 64, v5
	s_lshr_b32 s16, s12, 3
	s_add_i32 s2, s5, s2
	v_sub_u32_e32 v7, v7, v11
	s_ashr_i32 s3, s2, 31
	s_bfe_i64 s[24:25], s[16:17], 0x100000
	v_lshlrev_b32_e32 v10, 5, v6
	v_ashrrev_i16_sdwa v7, v12, sext(v7) dst_sel:DWORD dst_unused:UNUSED_PAD src0_sel:DWORD src1_sel:BYTE_0
	s_lshl_b64 s[12:13], s[2:3], 19
	s_lshl_b64 s[24:25], s[24:25], 19
	v_and_b32_e32 v10, 32, v10
	v_bfe_i32 v7, v7, 0, 16
	s_add_u32 s40, s8, s24
	v_add_lshl_u32 v10, v10, v7, 1
	s_addc_u32 s41, s9, s25
	s_add_i32 s3, s10, 0
	v_lshl_add_u32 v134, v9, 11, v10
	s_add_i32 m0, s3, 0x10000
	v_lshl_add_u32 v136, v8, 11, v10
	global_load_lds_dwordx4 v134, s[40:41]
	s_add_i32 m0, s3, 0x12000
	s_add_u32 s28, s66, s12
	global_load_lds_dwordx4 v130, s[40:41]
	s_addc_u32 s29, s67, s13
	s_mov_b32 m0, s3
	s_add_i32 s5, s3, 0x2000
	global_load_lds_dwordx4 v136, s[28:29]
	s_mov_b32 m0, s5
	s_add_u32 s12, s40, 0x40000
	global_load_lds_dwordx4 v132, s[28:29]
	s_addc_u32 s13, s41, 0
	s_add_i32 m0, s3, 0x14000
	s_nop 0
	global_load_lds_dwordx4 v134, s[12:13]
	s_add_i32 m0, s3, 0x16000
	s_add_u32 s24, s28, 0x40000
	global_load_lds_dwordx4 v130, s[12:13]
	s_addc_u32 s25, s29, 0
	s_add_i32 s12, s3, 0x4000
	s_mov_b32 m0, s12
	s_add_i32 s13, s3, 0x6000
	global_load_lds_dwordx4 v136, s[24:25]
	s_mov_b32 m0, s13
	s_cmp_lg_u32 s17, 1
	global_load_lds_dwordx4 v132, s[24:25]
	s_cbranch_scc1 .LBB0_474
	s_barrier

;     __host__ __device__ bool next(int i, Unit& u) const {
;         const long L = (long)i * G + c; if (L >= nwg) return false;
;         int wgid = (int)L; { const int q = nwg / NXCD, r = nwg % NXCD, xcd = wgid % NXCD, off = wgid / NXCD; wgid = (xcd < r ? xcd * (q + 1) : r * (q + 1) + (xcd - r) * q) + off; }
;         const int nig = WGM * nN, gid = wgid / nig, fm = gid * WGM, gsz = (nM - fm) < WGM ? (nM - fm) : WGM;
;         u.pm = fm + ((wgid % nig) % gsz); u.pn = (wgid % nig) / gsz; u.kh = -1; return true;
; template <class Epi, class Sched>
; __device__ __forceinline__ void gemm_phase(PG8_LAS unsigned char* lds, const Gemm g, const Sched& S, const Epi& E) {
;     ...
;     for (;;) {
;         const bool has_next = S.next(ui + 1, nxt);
;         int ncnt = nt; size_t nk = 0;
;         if constexpr (Sched::SPLIT) { if (has_next) { int k0_, kn_; S.krange(nxt, nt, k0_, kn_); ncnt = kn_; nk = (size_t)k0_ * kstep; } }
;         const char* nA = has_next ? (const char*)g.A + (size_t)nxt.pm * tstep + nk : cA; const char* nB = has_next ? (const char*)g.Bt + (size_t)nxt.pn * tstep + nk : cB;
;         for (int t = 0; t < cnt; t += 2) {
;             const bool last = (t == cnt - 2);
;             const char* a1 = cA + (size_t)(t + 1) * kstep;
;             const char* a2 = last ? nA : cA + (size_t)(t + 2) * kstep; const char* b2 = last ? nB : cB + (size_t)(t + 2) * kstep;
;             const char* a3 = a2 + kstep; const char* b3 = b2 + kstep;
;             if (last && has_next) S.a_ready(nxt);
;             PG8_LDB(B0, 0, 0); PG8_SCHED; PG8_LDA(At, 0, 0); PG8_STAGE(PG8_SA(1, 1), a1 + hstep, voffA);
;             PG8_WAIT_L(8); PG8_BAR; PG8_WAIT_L(0); PG8_MMA(0, 0, At, B0); PG8_BAR; PG8_SCHED;
;             PG8_LDB(B1, 0, 1); PG8_STAGE(PG8_SB(0, 0), b2, voffB);
;             PG8_BAR; PG8_WAIT_L(0); PG8_MMA(0, 1, At, B1); PG8_BAR;
;             PG8_LDA(At, 0, 1); PG8_STAGE(PG8_SA(0, 0), a2, voffA);
;             PG8_BAR; PG8_WAIT_L(0); PG8_MMA(1, 0, At, B0); PG8_BAR; PG8_SCHED;
;             PG8_STAGE(PG8_SB(0, 1), b2 + hstep, voffB);
;             PG8_WAIT_V(6); PG8_BAR; PG8_MMA(1, 1, At, B1); PG8_BAR;
;             PG8_LDB(B0, 1, 0); PG8_SCHED; PG8_LDA(At, 1, 0); PG8_STAGE(PG8_SA(0, 1), a2 + hstep, voffA);
;             PG8_WAIT_L(8); PG8_BAR; PG8_WAIT_L(0); PG8_MMA(0, 0, At, B0); PG8_BAR; PG8_SCHED;
;             PG8_LDB(B1, 1, 1); PG8_STAGE(PG8_SB(1, 0), b3, voffB);
.LBB0_475:
	s_add_i32 s48, s48, 1
	s_mul_i32 s17, s48, s33
	s_mul_hi_u32 s18, s48, s58
	s_add_i32 s18, s18, s17
	s_mul_i32 s17, s48, s58
	s_add_u32 s24, s17, s6
	s_addc_u32 s25, s18, s11
	v_mov_b64_e32 v[2:3], 0x47f
	v_cmp_gt_i64_e64 s[38:39], s[24:25], v[2:3]
	s_and_b64 vcc, exec, s[38:39]
	s_cbranch_vccnz .LBB0_477
	s_ashr_i32 s16, s24, 31
	s_lshr_b32 s16, s16, 29
	s_add_i32 s16, s24, s16
	s_ashr_i32 s17, s16, 3
	s_and_b32 s16, s16, -8
	s_sub_i32 s16, s24, s16
	s_cmp_lt_i32 s16, 0
	s_movk_i32 s18, 0x91
	s_cselect_b32 s18, s18, 0x90
	s_mul_i32 s16, s16, s18
	s_add_i32 s16, s16, s17
	s_ashr_i32 s17, s16, 6
	s_nop 0
	s_nop 0
	s_nop 0
	s_lshl_b32 s18, s17, 3
	s_sub_i32 s19, 0x90, s18
	s_min_i32 s19, s19, 8
	s_abs_i32 s20, s19
	v_cvt_f32_u32_e32 v2, s20
	s_sub_i32 s26, 0, s20
	s_mulk_i32 s17, 0x40
	s_sub_i32 s17, s16, s17
	v_rcp_iflag_f32_e32 v2, v2
	s_abs_i32 s16, s17
	s_xor_b32 s21, s17, s19
	s_ashr_i32 s21, s21, 31
	v_mul_f32_e32 v2, 0x4f7ffffe, v2
	v_cvt_u32_f32_e32 v2, v2
	s_nop 0
	v_readfirstlane_b32 s27, v2
	s_mul_i32 s26, s26, s27
	s_mul_hi_u32 s26, s27, s26
	s_add_i32 s27, s27, s26
	s_mul_hi_u32 s26, s16, s27
	s_mul_i32 s27, s26, s20
	s_sub_i32 s16, s16, s27
	s_add_i32 s42, s26, 1
	s_sub_i32 s27, s16, s20
	s_cmp_ge_u32 s16, s20
	s_cselect_b32 s26, s42, s26
	s_cselect_b32 s16, s27, s16
	s_add_i32 s27, s26, 1
	s_cmp_ge_u32 s16, s20
	s_cselect_b32 s16, s27, s26
	s_xor_b32 s16, s16, s21
	s_sub_i32 s16, s16, s21
	s_mul_i32 s19, s16, s19
	s_sub_i32 s17, s17, s19
	s_add_i32 s20, s18, s17
.LBB0_477:
	v_mov_b64_e32 v[2:3], 0x480
	s_ashr_i32 s21, s20, 31
	v_cmp_lt_i64_e32 vcc, s[24:25], v[2:3]
	s_lshl_b64 s[24:25], s[20:21], 19
	s_add_u32 s24, s66, s24
	s_addc_u32 s25, s67, s25
	s_and_b64 s[26:27], vcc, exec
	s_cselect_b32 s21, s25, s29
	s_cselect_b32 s50, s24, s28
	s_ashr_i32 s17, s16, 31
	s_lshl_b64 s[26:27], s[16:17], 19
	s_add_u32 s26, s8, s26
	s_addc_u32 s27, s9, s27
	s_and_b64 s[42:43], vcc, exec
	s_cselect_b32 s17, s27, s41
	s_cselect_b32 s51, s26, s40
	s_add_u32 s28, s28, 0x40080
	s_addc_u32 s29, s29, 0
	s_add_u32 s52, s40, 0x100
	v_mov_b32_e32 v2, 0
	s_addc_u32 s53, s41, 0
	s_mov_b32 s54, -2
	v_mov_b32_e32 v3, v2
	v_mov_b32_e32 v4, v2
	v_mov_b32_e32 v5, v2
	v_mov_b32_e32 v6, v2
	v_mov_b32_e32 v7, v2
	v_mov_b32_e32 v8, v2
	v_mov_b32_e32 v9, v2
	v_mov_b32_e32 v10, v2
	v_mov_b32_e32 v11, v2
	v_mov_b32_e32 v12, v2
	v_mov_b32_e32 v13, v2
	v_mov_b32_e32 v14, v2
	v_mov_b32_e32 v15, v2
	v_mov_b32_e32 v16, v2
	v_mov_b32_e32 v17, v2
	v_mov_b32_e32 v26, v2
	v_mov_b32_e32 v27, v2
	v_mov_b32_e32 v28, v2
	v_mov_b32_e32 v29, v2
	v_mov_b32_e32 v30, v2
	v_mov_b32_e32 v31, v2
	v_mov_b32_e32 v32, v2
	v_mov_b32_e32 v33, v2
	v_mov_b32_e32 v42, v2
	v_mov_b32_e32 v43, v2
	v_mov_b32_e32 v44, v2
	v_mov_b32_e32 v45, v2
	v_mov_b32_e32 v46, v2
	v_mov_b32_e32 v47, v2
	v_mov_b32_e32 v48, v2
	v_mov_b32_e32 v49, v2
	v_mov_b32_e32 v18, v2
	v_mov_b32_e32 v19, v2
	v_mov_b32_e32 v20, v2
	v_mov_b32_e32 v21, v2
	v_mov_b32_e32 v22, v2
	v_mov_b32_e32 v23, v2
	v_mov_b32_e32 v24, v2
	v_mov_b32_e32 v25, v2
	v_mov_b32_e32 v34, v2
	v_mov_b32_e32 v35, v2
	v_mov_b32_e32 v36, v2
	v_mov_b32_e32 v37, v2
	v_mov_b32_e32 v38, v2
	v_mov_b32_e32 v39, v2
	v_mov_b32_e32 v40, v2
	v_mov_b32_e32 v41, v2
	v_mov_b32_e32 v50, v2
	v_mov_b32_e32 v51, v2
	v_mov_b32_e32 v52, v2
	v_mov_b32_e32 v53, v2
	v_mov_b32_e32 v54, v2
	v_mov_b32_e32 v55, v2
	v_mov_b32_e32 v56, v2
	v_mov_b32_e32 v57, v2
	v_mov_b32_e32 v58, v2
	v_mov_b32_e32 v59, v2
	v_mov_b32_e32 v60, v2
	v_mov_b32_e32 v61, v2
	v_mov_b32_e32 v62, v2
	v_mov_b32_e32 v63, v2
	v_mov_b32_e32 v64, v2
	v_mov_b32_e32 v65, v2
	v_mov_b32_e32 v66, v2
	v_mov_b32_e32 v67, v2
	v_mov_b32_e32 v68, v2
	v_mov_b32_e32 v69, v2
	v_mov_b32_e32 v70, v2
	v_mov_b32_e32 v71, v2
	v_mov_b32_e32 v72, v2
	v_mov_b32_e32 v73, v2
	v_mov_b32_e32 v74, v2
	v_mov_b32_e32 v75, v2
	v_mov_b32_e32 v76, v2
	v_mov_b32_e32 v77, v2
	v_mov_b32_e32 v78, v2
	v_mov_b32_e32 v79, v2
	v_mov_b32_e32 v80, v2
	v_mov_b32_e32 v81, v2
	v_mov_b32_e32 v90, v2
	v_mov_b32_e32 v91, v2
	v_mov_b32_e32 v92, v2
	v_mov_b32_e32 v93, v2
	v_mov_b32_e32 v94, v2
	v_mov_b32_e32 v95, v2
	v_mov_b32_e32 v96, v2
	v_mov_b32_e32 v97, v2
	v_mov_b32_e32 v106, v2
	v_mov_b32_e32 v107, v2
	v_mov_b32_e32 v108, v2
	v_mov_b32_e32 v109, v2
	v_mov_b32_e32 v110, v2
	v_mov_b32_e32 v111, v2
	v_mov_b32_e32 v112, v2
	v_mov_b32_e32 v113, v2
	v_mov_b32_e32 v82, v2
	v_mov_b32_e32 v83, v2
	v_mov_b32_e32 v84, v2
	v_mov_b32_e32 v85, v2
	v_mov_b32_e32 v86, v2
	v_mov_b32_e32 v87, v2
	v_mov_b32_e32 v88, v2
	v_mov_b32_e32 v89, v2
	v_mov_b32_e32 v98, v2
	v_mov_b32_e32 v99, v2
	v_mov_b32_e32 v100, v2
	v_mov_b32_e32 v101, v2
	v_mov_b32_e32 v102, v2
	v_mov_b32_e32 v103, v2
	v_mov_b32_e32 v104, v2
	v_mov_b32_e32 v105, v2
	v_mov_b32_e32 v114, v2
	v_mov_b32_e32 v115, v2
	v_mov_b32_e32 v116, v2
	v_mov_b32_e32 v117, v2
	v_mov_b32_e32 v118, v2
	v_mov_b32_e32 v119, v2
	v_mov_b32_e32 v120, v2
	v_mov_b32_e32 v121, v2
	v_mov_b32_e32 v122, v2
	v_mov_b32_e32 v123, v2
	v_mov_b32_e32 v124, v2
	v_mov_b32_e32 v125, v2
	v_mov_b32_e32 v126, v2
	v_mov_b32_e32 v127, v2
	v_mov_b32_e32 v128, v2
	v_mov_b32_e32 v129, v2

; __device__ __forceinline__ int otid() { int t = threadIdx.x; asm volatile("" : "+v"(t)); return t; }
; #define PG8_LAS __attribute__((address_space(3)))
; template <class Epi, class Sched>
; __device__ __forceinline__ void gemm_phase(PG8_LAS unsigned char* lds, const Gemm g, const Sched& S, const Epi& E) {
;     const int tid = otid(), wid = __builtin_amdgcn_readfirstlane(tid >> 6), lane = tid & 63, wr = wid >> 2, wc = wid & 3, fr = lane & 15, fq = lane >> 4;
;     const int K = g.K, nt = K / BK;
;     unsigned voffA[2], voffB[2];
; #pragma unroll
;     for (int i = 0; i < 2; ++i) { int R, C; stage_rc(tid * 16 + i * 8192, R, C); const int Rb = Epi::PERM ? ((R & ~31) + perm32(R & 31)) : R;
;         voffA[i] = (unsigned)(R * K + C) * 2u; voffB[i] = (unsigned)(Rb * K + C) * 2u; }
;     const size_t kstep = (size_t)(BK * 2);
;     const size_t hstep = (size_t)HALF * K * 2;
;     const size_t tstep = 2 * hstep;
;     const unsigned ldsw = (unsigned)wid * 1024u;
;     const int foff = lds_byte(fr, fq * 8); const int ua = wr * 8192, ub = wc * 4096;
.LBB0_535:
	s_or_b64 exec, exec, s[2:3]
	v_mov_b32_e32 v10, v253
	s_waitcnt lgkmcnt(0)
	s_barrier
	v_readlane_b32 s41, v255, 45
	s_mul_i32 s42, s41, 0x480000
	s_add_u32 s38, s56, s42
	s_addc_u32 s39, s57, 0
	s_add_u32 s38, s38, 0x1598000
	s_addc_u32 s39, s39, 0
	v_lshrrev_b32_e32 v50, 4, v253
	v_and_b32_e32 v51, 15, v253
	v_and_b32_e32 v52, 15, v50
	v_lshrrev_b32_e32 v53, 2, v52
	v_lshlrev_b32_e32 v53, 3, v53
	v_and_b32_e32 v54, 3, v52
	v_add_u32_e32 v53, v53, v54
	v_lshrrev_b32_e32 v54, 4, v50
	v_lshl_add_u32 v53, v54, 2, v53
	v_lshlrev_b32_e32 v53, 11, v53
	v_lshl_add_u32 v53, v51, 4, v53
	v_mul_u32_u24_e32 v54, 0x820, v50
	v_lshl_add_u32 v54, v51, 4, v54
	global_load_dwordx4 v[80:83], v53, s[38:39]
	global_load_dwordx4 v[84:87], v53, s[38:39] offset:256
	global_load_dwordx4 v[88:91], v53, s[38:39] offset:512
	global_load_dwordx4 v[92:95], v53, s[38:39] offset:768
	global_load_dwordx4 v[96:99], v53, s[38:39] offset:1024
	global_load_dwordx4 v[100:103], v53, s[38:39] offset:1280
	global_load_dwordx4 v[104:107], v53, s[38:39] offset:1536
	global_load_dwordx4 v[108:111], v53, s[38:39] offset:1792
	s_waitcnt vmcnt(0)
	ds_write_b128 v54, v[80:83]
	ds_write_b128 v54, v[84:87] offset:256
	ds_write_b128 v54, v[88:91] offset:512
	ds_write_b128 v54, v[92:95] offset:768
	ds_write_b128 v54, v[96:99] offset:1024
	ds_write_b128 v54, v[100:103] offset:1280
	ds_write_b128 v54, v[104:107] offset:1536
	ds_write_b128 v54, v[108:111] offset:1792
	s_waitcnt lgkmcnt(0)
	s_barrier
	v_and_b32_e32 v55, 63, v253
	v_and_b32_e32 v56, 15, v55
	v_lshrrev_b32_e32 v57, 4, v55
	v_lshlrev_b32_e32 v50, 4, v57
	v_lshl_add_u32 v58, v56, 11, v50
	v_mul_u32_u24_e32 v61, 0x820, v56
	v_add_u32_e32 v61, v61, v50
	v_mul_u32_u24_e32 v62, 0x1200, v56
	v_add_u32_e32 v62, v62, v50
	v_add_u32_e32 v62, 0x1000, v62
	v_readfirstlane_b32 s40, v253
	s_lshr_b32 s40, s40, 6
	s_lshl_b32 s41, s63, 3
	s_add_i32 s41, s41, s40
	s_lshl_b32 s42, s41, 15
	s_mul_i32 s43, s41, 0x12000
	v_add_u32_e32 v60, s42, v58
	v_add_u32_e32 v63, s43, v62
	global_load_dwordx4 v[80:83], v60, s[66:67]
	global_load_dwordx4 v[84:87], v60, s[66:67] offset:64
	global_load_dwordx4 v[88:91], v60, s[66:67] offset:128
	global_load_dwordx4 v[92:95], v60, s[66:67] offset:192
	global_load_dwordx4 v[96:99], v60, s[66:67] offset:256
	global_load_dwordx4 v[100:103], v60, s[66:67] offset:320
	global_load_dwordx4 v[104:107], v60, s[66:67] offset:384
	global_load_dwordx4 v[108:111], v60, s[66:67] offset:448
	global_load_dwordx4 v[112:115], v60, s[66:67] offset:512
	global_load_dwordx4 v[116:119], v60, s[66:67] offset:576
	global_load_dwordx4 v[120:123], v60, s[66:67] offset:640
	global_load_dwordx4 v[124:127], v60, s[66:67] offset:704
	global_load_dwordx4 v[128:131], v60, s[66:67] offset:768
	global_load_dwordx4 v[132:135], v60, s[66:67] offset:832
	global_load_dwordx4 v[136:139], v60, s[66:67] offset:896
	global_load_dwordx4 v[140:143], v60, s[66:67] offset:960
	global_load_dwordx4 v[144:147], v60, s[66:67] offset:1024
	global_load_dwordx4 v[148:151], v60, s[66:67] offset:1088
	global_load_dwordx4 v[156:159], v60, s[66:67] offset:1152
	global_load_dwordx4 v[160:163], v60, s[66:67] offset:1216
	global_load_dwordx4 v[164:167], v60, s[66:67] offset:1280
	global_load_dwordx4 v[168:171], v60, s[66:67] offset:1344
	global_load_dwordx4 v[172:175], v60, s[66:67] offset:1408
	global_load_dwordx4 v[176:179], v60, s[66:67] offset:1472
	global_load_dwordx4 v[180:183], v60, s[66:67] offset:1536
	global_load_dwordx4 v[184:187], v60, s[66:67] offset:1600
	global_load_dwordx4 v[188:191], v60, s[66:67] offset:1664
	global_load_dwordx4 v[192:195], v60, s[66:67] offset:1728
	global_load_dwordx4 v[196:199], v60, s[66:67] offset:1792
	global_load_dwordx4 v[200:203], v60, s[66:67] offset:1856
	global_load_dwordx4 v[204:207], v60, s[66:67] offset:1920
	global_load_dwordx4 v[224:227], v60, s[66:67] offset:1984
	v_mov_b32_e32 v42, 0
	v_mov_b32_e32 v43, 0
	v_mov_b32_e32 v44, 0
	v_mov_b32_e32 v45, 0
	v_mov_b32_e32 v46, 0
	v_mov_b32_e32 v47, 0
	v_mov_b32_e32 v48, 0
	v_mov_b32_e32 v49, 0
	ds_read_b128 v[228:231], v61 offset:0
	ds_read_b128 v[232:235], v61 offset:33280
	ds_read_b128 v[236:239], v61 offset:64
	ds_read_b128 v[240:243], v61 offset:33344
	ds_read_b128 v[244:247], v61 offset:128
	ds_read_b128 v[248:251], v61 offset:33408
	ds_read_b128 v[34:37], v61 offset:192
	ds_read_b128 v[38:41], v61 offset:33472
	s_waitcnt vmcnt(31)
	s_waitcnt lgkmcnt(6)
	v_mfma_f32_16x16x32_bf16 v[42:45], v[228:231], v[80:83], v[42:45]
	v_mfma_f32_16x16x32_bf16 v[46:49], v[232:235], v[80:83], v[46:49]
	ds_read_b128 v[228:231], v61 offset:256
	ds_read_b128 v[232:235], v61 offset:33536
	s_waitcnt vmcnt(30)
	s_waitcnt lgkmcnt(6)
	v_mfma_f32_16x16x32_bf16 v[42:45], v[236:239], v[84:87], v[42:45]
	v_mfma_f32_16x16x32_bf16 v[46:49], v[240:243], v[84:87], v[46:49]
	ds_read_b128 v[236:239], v61 offset:320
	ds_read_b128 v[240:243], v61 offset:33600
	s_waitcnt vmcnt(29)
	s_waitcnt lgkmcnt(6)
	v_mfma_f32_16x16x32_bf16 v[42:45], v[244:247], v[88:91], v[42:45]
	v_mfma_f32_16x16x32_bf16 v[46:49], v[248:251], v[88:91], v[46:49]
	ds_read_b128 v[244:247], v61 offset:384
	ds_read_b128 v[248:251], v61 offset:33664
	s_waitcnt vmcnt(28)
	s_waitcnt lgkmcnt(6)
	v_mfma_f32_16x16x32_bf16 v[42:45], v[34:37], v[92:95], v[42:45]
	v_mfma_f32_16x16x32_bf16 v[46:49], v[38:41], v[92:95], v[46:49]
	ds_read_b128 v[34:37], v61 offset:448
	ds_read_b128 v[38:41], v61 offset:33728
	s_waitcnt vmcnt(27)
	s_waitcnt lgkmcnt(6)
	v_mfma_f32_16x16x32_bf16 v[42:45], v[228:231], v[96:99], v[42:45]
	v_mfma_f32_16x16x32_bf16 v[46:49], v[232:235], v[96:99], v[46:49]
	ds_read_b128 v[228:231], v61 offset:512
	ds_read_b128 v[232:235], v61 offset:33792
	s_waitcnt vmcnt(26)
; __device__ __forceinline__ unsigned cvt_pk_bf16(float lo, float hi) { const f32x2c f = {lo, hi}; return __builtin_bit_cast(unsigned, __builtin_convertvector(f, bf16x2c)); }
;     __device__ __forceinline__ void operator()(const f32x4 (&acc)[2][2][4][2], const Unit& u, int wr, int wc, int fr, int fq) const {
;     ...
;                 for (int bj = 0; bj < 2; ++bj) { const f32x4 v0 = acc[ai][bj][m][0], v1 = acc[ai][bj][m][1];
;                     u32x4 w; w.x = cvt_pk_bf16(v0[0], v0[1]); w.y = cvt_pk_bf16(v0[2], v0[3]); w.z = cvt_pk_bf16(v1[0], v1[1]); w.w = cvt_pk_bf16(v1[2], v1[3]);
;                     *(u32x4*)(rowp + bj * HALF) = w; } }
	s_waitcnt lgkmcnt(6)
	v_mfma_f32_16x16x32_bf16 v[42:45], v[236:239], v[100:103], v[42:45]
	v_mfma_f32_16x16x32_bf16 v[46:49], v[240:243], v[100:103], v[46:49]
	ds_read_b128 v[236:239], v61 offset:576
	ds_read_b128 v[240:243], v61 offset:33856
	s_waitcnt vmcnt(25)
	s_waitcnt lgkmcnt(6)
	v_mfma_f32_16x16x32_bf16 v[42:45], v[244:247], v[104:107], v[42:45]
	v_mfma_f32_16x16x32_bf16 v[46:49], v[248:251], v[104:107], v[46:49]
	ds_read_b128 v[244:247], v61 offset:640
	ds_read_b128 v[248:251], v61 offset:33920
	s_waitcnt vmcnt(24)
	s_waitcnt lgkmcnt(6)
	v_mfma_f32_16x16x32_bf16 v[42:45], v[34:37], v[108:111], v[42:45]
	v_mfma_f32_16x16x32_bf16 v[46:49], v[38:41], v[108:111], v[46:49]
	ds_read_b128 v[34:37], v61 offset:704
	ds_read_b128 v[38:41], v61 offset:33984
	s_waitcnt vmcnt(23)
	s_waitcnt lgkmcnt(6)
	v_mfma_f32_16x16x32_bf16 v[42:45], v[228:231], v[112:115], v[42:45]
	v_mfma_f32_16x16x32_bf16 v[46:49], v[232:235], v[112:115], v[46:49]
	ds_read_b128 v[228:231], v61 offset:768
	ds_read_b128 v[232:235], v61 offset:34048
	s_waitcnt vmcnt(22)
	s_waitcnt lgkmcnt(6)
	v_mfma_f32_16x16x32_bf16 v[42:45], v[236:239], v[116:119], v[42:45]
	v_mfma_f32_16x16x32_bf16 v[46:49], v[240:243], v[116:119], v[46:49]
	ds_read_b128 v[236:239], v61 offset:832
	ds_read_b128 v[240:243], v61 offset:34112
	s_waitcnt vmcnt(21)
	s_waitcnt lgkmcnt(6)
	v_mfma_f32_16x16x32_bf16 v[42:45], v[244:247], v[120:123], v[42:45]
	v_mfma_f32_16x16x32_bf16 v[46:49], v[248:251], v[120:123], v[46:49]
	ds_read_b128 v[244:247], v61 offset:896
	ds_read_b128 v[248:251], v61 offset:34176
	s_waitcnt vmcnt(20)
	s_waitcnt lgkmcnt(6)
	v_mfma_f32_16x16x32_bf16 v[42:45], v[34:37], v[124:127], v[42:45]
	v_mfma_f32_16x16x32_bf16 v[46:49], v[38:41], v[124:127], v[46:49]
	ds_read_b128 v[34:37], v61 offset:960
	ds_read_b128 v[38:41], v61 offset:34240
	s_waitcnt vmcnt(19)
	s_waitcnt lgkmcnt(6)
	v_mfma_f32_16x16x32_bf16 v[42:45], v[228:231], v[128:131], v[42:45]
	v_mfma_f32_16x16x32_bf16 v[46:49], v[232:235], v[128:131], v[46:49]
	ds_read_b128 v[228:231], v61 offset:1024
	ds_read_b128 v[232:235], v61 offset:34304
	s_waitcnt vmcnt(18)
	s_waitcnt lgkmcnt(6)
	v_mfma_f32_16x16x32_bf16 v[42:45], v[236:239], v[132:135], v[42:45]
	v_mfma_f32_16x16x32_bf16 v[46:49], v[240:243], v[132:135], v[46:49]
	ds_read_b128 v[236:239], v61 offset:1088
	ds_read_b128 v[240:243], v61 offset:34368
	s_waitcnt vmcnt(17)
	s_waitcnt lgkmcnt(6)
	v_mfma_f32_16x16x32_bf16 v[42:45], v[244:247], v[136:139], v[42:45]
	v_mfma_f32_16x16x32_bf16 v[46:49], v[248:251], v[136:139], v[46:49]
	ds_read_b128 v[244:247], v61 offset:1152
	ds_read_b128 v[248:251], v61 offset:34432
	s_waitcnt vmcnt(16)
	s_waitcnt lgkmcnt(6)
	v_mfma_f32_16x16x32_bf16 v[42:45], v[34:37], v[140:143], v[42:45]
	v_mfma_f32_16x16x32_bf16 v[46:49], v[38:41], v[140:143], v[46:49]
	ds_read_b128 v[34:37], v61 offset:1216
	ds_read_b128 v[38:41], v61 offset:34496
	s_waitcnt vmcnt(15)
	s_waitcnt lgkmcnt(6)
	v_mfma_f32_16x16x32_bf16 v[42:45], v[228:231], v[144:147], v[42:45]
	v_mfma_f32_16x16x32_bf16 v[46:49], v[232:235], v[144:147], v[46:49]
	ds_read_b128 v[228:231], v61 offset:1280
	ds_read_b128 v[232:235], v61 offset:34560
	s_waitcnt vmcnt(14)
	s_waitcnt lgkmcnt(6)
	v_mfma_f32_16x16x32_bf16 v[42:45], v[236:239], v[148:151], v[42:45]
	v_mfma_f32_16x16x32_bf16 v[46:49], v[240:243], v[148:151], v[46:49]
	ds_read_b128 v[236:239], v61 offset:1344
	ds_read_b128 v[240:243], v61 offset:34624
	s_waitcnt vmcnt(13)
	s_waitcnt lgkmcnt(6)
	v_mfma_f32_16x16x32_bf16 v[42:45], v[244:247], v[156:159], v[42:45]
	v_mfma_f32_16x16x32_bf16 v[46:49], v[248:251], v[156:159], v[46:49]
	ds_read_b128 v[244:247], v61 offset:1408
	ds_read_b128 v[248:251], v61 offset:34688
	s_waitcnt vmcnt(12)
	s_waitcnt lgkmcnt(6)
	v_mfma_f32_16x16x32_bf16 v[42:45], v[34:37], v[160:163], v[42:45]
	v_mfma_f32_16x16x32_bf16 v[46:49], v[38:41], v[160:163], v[46:49]
	ds_read_b128 v[34:37], v61 offset:1472
	ds_read_b128 v[38:41], v61 offset:34752
	s_waitcnt vmcnt(11)
	s_waitcnt lgkmcnt(6)
	v_mfma_f32_16x16x32_bf16 v[42:45], v[228:231], v[164:167], v[42:45]
	v_mfma_f32_16x16x32_bf16 v[46:49], v[232:235], v[164:167], v[46:49]
	ds_read_b128 v[228:231], v61 offset:1536
	ds_read_b128 v[232:235], v61 offset:34816
	s_waitcnt vmcnt(10)
	s_waitcnt lgkmcnt(6)
	v_mfma_f32_16x16x32_bf16 v[42:45], v[236:239], v[168:171], v[42:45]
	v_mfma_f32_16x16x32_bf16 v[46:49], v[240:243], v[168:171], v[46:49]
	ds_read_b128 v[236:239], v61 offset:1600
	ds_read_b128 v[240:243], v61 offset:34880
	s_waitcnt vmcnt(9)
	s_waitcnt lgkmcnt(6)
	v_mfma_f32_16x16x32_bf16 v[42:45], v[244:247], v[172:175], v[42:45]
	v_mfma_f32_16x16x32_bf16 v[46:49], v[248:251], v[172:175], v[46:49]
	ds_read_b128 v[244:247], v61 offset:1664
	ds_read_b128 v[248:251], v61 offset:34944
	s_waitcnt vmcnt(8)
	s_waitcnt lgkmcnt(6)
	v_mfma_f32_16x16x32_bf16 v[42:45], v[34:37], v[176:179], v[42:45]
	v_mfma_f32_16x16x32_bf16 v[46:49], v[38:41], v[176:179], v[46:49]
	ds_read_b128 v[34:37], v61 offset:1728
	ds_read_b128 v[38:41], v61 offset:35008
	s_waitcnt vmcnt(7)
	s_waitcnt lgkmcnt(6)
	v_mfma_f32_16x16x32_bf16 v[42:45], v[228:231], v[180:183], v[42:45]
	v_mfma_f32_16x16x32_bf16 v[46:49], v[232:235], v[180:183], v[46:49]
	ds_read_b128 v[228:231], v61 offset:1792
	ds_read_b128 v[232:235], v61 offset:35072
	s_waitcnt vmcnt(6)
	s_waitcnt lgkmcnt(6)
	v_mfma_f32_16x16x32_bf16 v[42:45], v[236:239], v[184:187], v[42:45]
	v_mfma_f32_16x16x32_bf16 v[46:49], v[240:243], v[184:187], v[46:49]
	ds_read_b128 v[236:239], v61 offset:1856
	ds_read_b128 v[240:243], v61 offset:35136
	s_waitcnt vmcnt(5)
	s_waitcnt lgkmcnt(6)
	v_mfma_f32_16x16x32_bf16 v[42:45], v[244:247], v[188:191], v[42:45]
	v_mfma_f32_16x16x32_bf16 v[46:49], v[248:251], v[188:191], v[46:49]
	ds_read_b128 v[244:247], v61 offset:1920
	ds_read_b128 v[248:251], v61 offset:35200
	s_waitcnt vmcnt(4)
	s_waitcnt lgkmcnt(6)
	v_mfma_f32_16x16x32_bf16 v[42:45], v[34:37], v[192:195], v[42:45]
	v_mfma_f32_16x16x32_bf16 v[46:49], v[38:41], v[192:195], v[46:49]
	ds_read_b128 v[34:37], v61 offset:1984
	ds_read_b128 v[38:41], v61 offset:35264
	s_waitcnt vmcnt(3)
	s_waitcnt lgkmcnt(6)
	v_mfma_f32_16x16x32_bf16 v[42:45], v[228:231], v[196:199], v[42:45]
	v_mfma_f32_16x16x32_bf16 v[46:49], v[232:235], v[196:199], v[46:49]
	s_waitcnt vmcnt(2)
	s_waitcnt lgkmcnt(4)
	v_mfma_f32_16x16x32_bf16 v[42:45], v[236:239], v[200:203], v[42:45]
	v_mfma_f32_16x16x32_bf16 v[46:49], v[240:243], v[200:203], v[46:49]
	s_waitcnt vmcnt(1)
	s_waitcnt lgkmcnt(2)
	v_mfma_f32_16x16x32_bf16 v[42:45], v[244:247], v[204:207], v[42:45]
	v_mfma_f32_16x16x32_bf16 v[46:49], v[248:251], v[204:207], v[46:49]
	s_waitcnt vmcnt(0)
	s_waitcnt lgkmcnt(0)
	v_mfma_f32_16x16x32_bf16 v[42:45], v[34:37], v[224:227], v[42:45]
	v_mfma_f32_16x16x32_bf16 v[46:49], v[38:41], v[224:227], v[46:49]
	s_nop 7
	s_nop 1
	v_cvt_pk_bf16_f32 v64, v42, v43
	v_cvt_pk_bf16_f32 v65, v44, v45
	v_cvt_pk_bf16_f32 v66, v46, v47
	v_cvt_pk_bf16_f32 v67, v48, v49
	global_store_dwordx4 v63, v[64:67], s[68:69]
	s_cmp_lg_u32 s40, 0
	s_cbranch_scc1 .Llg32_done
; __device__ __forceinline__ unsigned cvt_pk_bf16(float lo, float hi) { const f32x2c f = {lo, hi}; return __builtin_bit_cast(unsigned, __builtin_convertvector(f, bf16x2c)); }
;     __device__ __forceinline__ void operator()(const f32x4 (&acc)[2][2][4][2], const Unit& u, int wr, int wc, int fr, int fq) const {
;     ...
;                 for (int bj = 0; bj < 2; ++bj) { const f32x4 v0 = acc[ai][bj][m][0], v1 = acc[ai][bj][m][1];
;                     u32x4 w; w.x = cvt_pk_bf16(v0[0], v0[1]); w.y = cvt_pk_bf16(v0[2], v0[3]); w.z = cvt_pk_bf16(v1[0], v1[1]); w.w = cvt_pk_bf16(v1[2], v1[3]);
;                     *(u32x4*)(rowp + bj * HALF) = w; } }
	s_add_i32 s41, s63, 0x800
	s_lshl_b32 s42, s41, 15
	s_mul_i32 s43, s41, 0x12000
	v_add_u32_e32 v60, s42, v58
	v_add_u32_e32 v63, s43, v62
	global_load_dwordx4 v[80:83], v60, s[66:67]
	global_load_dwordx4 v[84:87], v60, s[66:67] offset:64
	global_load_dwordx4 v[88:91], v60, s[66:67] offset:128
	global_load_dwordx4 v[92:95], v60, s[66:67] offset:192
	global_load_dwordx4 v[96:99], v60, s[66:67] offset:256
	global_load_dwordx4 v[100:103], v60, s[66:67] offset:320
	global_load_dwordx4 v[104:107], v60, s[66:67] offset:384
	global_load_dwordx4 v[108:111], v60, s[66:67] offset:448
	global_load_dwordx4 v[112:115], v60, s[66:67] offset:512
	global_load_dwordx4 v[116:119], v60, s[66:67] offset:576
	global_load_dwordx4 v[120:123], v60, s[66:67] offset:640
	global_load_dwordx4 v[124:127], v60, s[66:67] offset:704
	global_load_dwordx4 v[128:131], v60, s[66:67] offset:768
	global_load_dwordx4 v[132:135], v60, s[66:67] offset:832
	global_load_dwordx4 v[136:139], v60, s[66:67] offset:896
	global_load_dwordx4 v[140:143], v60, s[66:67] offset:960
	global_load_dwordx4 v[144:147], v60, s[66:67] offset:1024
	global_load_dwordx4 v[148:151], v60, s[66:67] offset:1088
	global_load_dwordx4 v[156:159], v60, s[66:67] offset:1152
	global_load_dwordx4 v[160:163], v60, s[66:67] offset:1216
	global_load_dwordx4 v[164:167], v60, s[66:67] offset:1280
	global_load_dwordx4 v[168:171], v60, s[66:67] offset:1344
	global_load_dwordx4 v[172:175], v60, s[66:67] offset:1408
	global_load_dwordx4 v[176:179], v60, s[66:67] offset:1472
	global_load_dwordx4 v[180:183], v60, s[66:67] offset:1536
	global_load_dwordx4 v[184:187], v60, s[66:67] offset:1600
	global_load_dwordx4 v[188:191], v60, s[66:67] offset:1664
	global_load_dwordx4 v[192:195], v60, s[66:67] offset:1728
	global_load_dwordx4 v[196:199], v60, s[66:67] offset:1792
	global_load_dwordx4 v[200:203], v60, s[66:67] offset:1856
	global_load_dwordx4 v[204:207], v60, s[66:67] offset:1920
	global_load_dwordx4 v[224:227], v60, s[66:67] offset:1984
	v_mov_b32_e32 v42, 0
	v_mov_b32_e32 v43, 0
	v_mov_b32_e32 v44, 0
	v_mov_b32_e32 v45, 0
	v_mov_b32_e32 v46, 0
	v_mov_b32_e32 v47, 0
	v_mov_b32_e32 v48, 0
	v_mov_b32_e32 v49, 0
	ds_read_b128 v[228:231], v61 offset:0
	ds_read_b128 v[232:235], v61 offset:33280
	ds_read_b128 v[236:239], v61 offset:64
	ds_read_b128 v[240:243], v61 offset:33344
	ds_read_b128 v[244:247], v61 offset:128
	ds_read_b128 v[248:251], v61 offset:33408
	ds_read_b128 v[34:37], v61 offset:192
	ds_read_b128 v[38:41], v61 offset:33472
	s_waitcnt vmcnt(31)
	s_waitcnt lgkmcnt(6)
	v_mfma_f32_16x16x32_bf16 v[42:45], v[228:231], v[80:83], v[42:45]
	v_mfma_f32_16x16x32_bf16 v[46:49], v[232:235], v[80:83], v[46:49]
	ds_read_b128 v[228:231], v61 offset:256
	ds_read_b128 v[232:235], v61 offset:33536
	s_waitcnt vmcnt(30)
	s_waitcnt lgkmcnt(6)
	v_mfma_f32_16x16x32_bf16 v[42:45], v[236:239], v[84:87], v[42:45]
	v_mfma_f32_16x16x32_bf16 v[46:49], v[240:243], v[84:87], v[46:49]
	ds_read_b128 v[236:239], v61 offset:320
	ds_read_b128 v[240:243], v61 offset:33600
	s_waitcnt vmcnt(29)
	s_waitcnt lgkmcnt(6)
	v_mfma_f32_16x16x32_bf16 v[42:45], v[244:247], v[88:91], v[42:45]
	v_mfma_f32_16x16x32_bf16 v[46:49], v[248:251], v[88:91], v[46:49]
	ds_read_b128 v[244:247], v61 offset:384
	ds_read_b128 v[248:251], v61 offset:33664
	s_waitcnt vmcnt(28)
	s_waitcnt lgkmcnt(6)
	v_mfma_f32_16x16x32_bf16 v[42:45], v[34:37], v[92:95], v[42:45]
	v_mfma_f32_16x16x32_bf16 v[46:49], v[38:41], v[92:95], v[46:49]
	ds_read_b128 v[34:37], v61 offset:448
	ds_read_b128 v[38:41], v61 offset:33728
	s_waitcnt vmcnt(27)
	s_waitcnt lgkmcnt(6)
	v_mfma_f32_16x16x32_bf16 v[42:45], v[228:231], v[96:99], v[42:45]
	v_mfma_f32_16x16x32_bf16 v[46:49], v[232:235], v[96:99], v[46:49]
	ds_read_b128 v[228:231], v61 offset:512
	ds_read_b128 v[232:235], v61 offset:33792
	s_waitcnt vmcnt(26)
	s_waitcnt lgkmcnt(6)
	v_mfma_f32_16x16x32_bf16 v[42:45], v[236:239], v[100:103], v[42:45]
	v_mfma_f32_16x16x32_bf16 v[46:49], v[240:243], v[100:103], v[46:49]
	ds_read_b128 v[236:239], v61 offset:576
	ds_read_b128 v[240:243], v61 offset:33856
	s_waitcnt vmcnt(25)
	s_waitcnt lgkmcnt(6)
	v_mfma_f32_16x16x32_bf16 v[42:45], v[244:247], v[104:107], v[42:45]
	v_mfma_f32_16x16x32_bf16 v[46:49], v[248:251], v[104:107], v[46:49]
	ds_read_b128 v[244:247], v61 offset:640
	ds_read_b128 v[248:251], v61 offset:33920
	s_waitcnt vmcnt(24)
	s_waitcnt lgkmcnt(6)
	v_mfma_f32_16x16x32_bf16 v[42:45], v[34:37], v[108:111], v[42:45]
	v_mfma_f32_16x16x32_bf16 v[46:49], v[38:41], v[108:111], v[46:49]
	ds_read_b128 v[34:37], v61 offset:704
	ds_read_b128 v[38:41], v61 offset:33984
	s_waitcnt vmcnt(23)
	s_waitcnt lgkmcnt(6)
	v_mfma_f32_16x16x32_bf16 v[42:45], v[228:231], v[112:115], v[42:45]
	v_mfma_f32_16x16x32_bf16 v[46:49], v[232:235], v[112:115], v[46:49]
	ds_read_b128 v[228:231], v61 offset:768
	ds_read_b128 v[232:235], v61 offset:34048
	s_waitcnt vmcnt(22)
	s_waitcnt lgkmcnt(6)
	v_mfma_f32_16x16x32_bf16 v[42:45], v[236:239], v[116:119], v[42:45]
	v_mfma_f32_16x16x32_bf16 v[46:49], v[240:243], v[116:119], v[46:49]
	ds_read_b128 v[236:239], v61 offset:832
	ds_read_b128 v[240:243], v61 offset:34112
	s_waitcnt vmcnt(21)
	s_waitcnt lgkmcnt(6)
	v_mfma_f32_16x16x32_bf16 v[42:45], v[244:247], v[120:123], v[42:45]
	v_mfma_f32_16x16x32_bf16 v[46:49], v[248:251], v[120:123], v[46:49]
	ds_read_b128 v[244:247], v61 offset:896
	ds_read_b128 v[248:251], v61 offset:34176
	s_waitcnt vmcnt(20)
	s_waitcnt lgkmcnt(6)
	v_mfma_f32_16x16x32_bf16 v[42:45], v[34:37], v[124:127], v[42:45]
	v_mfma_f32_16x16x32_bf16 v[46:49], v[38:41], v[124:127], v[46:49]
	ds_read_b128 v[34:37], v61 offset:960
	ds_read_b128 v[38:41], v61 offset:34240
	s_waitcnt vmcnt(19)
; #define PIN(i) ((const float*)(const GASP float*)karg_q(i))
; __device__ __forceinline__ void p3_prep(const Params& P, int l) {
;     ...
;     { const float* nqg = PIN(9) + l * 64 + sub * 8; const float* nkg = PIN(10) + l * 64 + sub * 8;
; #pragma unroll
;       for (int j = 0; j < 8; ++j) { gA[j] = lane < 48 ? nqg[j] * NA_QSCALE : nkg[j]; gB[j] = nkg[j]; }
;       const float* gc = lane < 32 ? PIN(12) + l * 256 + lane * 8 : (lane < 48 ? PIN(14) + l * 128 + (lane - 32) * 8 : PIN(17) + l * 96 + 64 + ((lane - 48) & 3) * 8);
	s_waitcnt lgkmcnt(6)
	v_mfma_f32_16x16x32_bf16 v[42:45], v[228:231], v[128:131], v[42:45]
	v_mfma_f32_16x16x32_bf16 v[46:49], v[232:235], v[128:131], v[46:49]
	ds_read_b128 v[228:231], v61 offset:1024
	ds_read_b128 v[232:235], v61 offset:34304
	s_waitcnt vmcnt(18)
	s_waitcnt lgkmcnt(6)
	v_mfma_f32_16x16x32_bf16 v[42:45], v[236:239], v[132:135], v[42:45]
	v_mfma_f32_16x16x32_bf16 v[46:49], v[240:243], v[132:135], v[46:49]
	ds_read_b128 v[236:239], v61 offset:1088
	ds_read_b128 v[240:243], v61 offset:34368
	s_waitcnt vmcnt(17)
	s_waitcnt lgkmcnt(6)
	v_mfma_f32_16x16x32_bf16 v[42:45], v[244:247], v[136:139], v[42:45]
	v_mfma_f32_16x16x32_bf16 v[46:49], v[248:251], v[136:139], v[46:49]
	ds_read_b128 v[244:247], v61 offset:1152
	ds_read_b128 v[248:251], v61 offset:34432
	s_waitcnt vmcnt(16)
	s_waitcnt lgkmcnt(6)
	v_mfma_f32_16x16x32_bf16 v[42:45], v[34:37], v[140:143], v[42:45]
	v_mfma_f32_16x16x32_bf16 v[46:49], v[38:41], v[140:143], v[46:49]
	ds_read_b128 v[34:37], v61 offset:1216
	ds_read_b128 v[38:41], v61 offset:34496
	s_waitcnt vmcnt(15)
	s_waitcnt lgkmcnt(6)
	v_mfma_f32_16x16x32_bf16 v[42:45], v[228:231], v[144:147], v[42:45]
	v_mfma_f32_16x16x32_bf16 v[46:49], v[232:235], v[144:147], v[46:49]
	ds_read_b128 v[228:231], v61 offset:1280
	ds_read_b128 v[232:235], v61 offset:34560
	s_waitcnt vmcnt(14)
	s_waitcnt lgkmcnt(6)
	v_mfma_f32_16x16x32_bf16 v[42:45], v[236:239], v[148:151], v[42:45]
	v_mfma_f32_16x16x32_bf16 v[46:49], v[240:243], v[148:151], v[46:49]
	ds_read_b128 v[236:239], v61 offset:1344
	ds_read_b128 v[240:243], v61 offset:34624
	s_waitcnt vmcnt(13)
	s_waitcnt lgkmcnt(6)
	v_mfma_f32_16x16x32_bf16 v[42:45], v[244:247], v[156:159], v[42:45]
	v_mfma_f32_16x16x32_bf16 v[46:49], v[248:251], v[156:159], v[46:49]
	ds_read_b128 v[244:247], v61 offset:1408
	ds_read_b128 v[248:251], v61 offset:34688
	s_waitcnt vmcnt(12)
	s_waitcnt lgkmcnt(6)
	v_mfma_f32_16x16x32_bf16 v[42:45], v[34:37], v[160:163], v[42:45]
	v_mfma_f32_16x16x32_bf16 v[46:49], v[38:41], v[160:163], v[46:49]
	ds_read_b128 v[34:37], v61 offset:1472
	ds_read_b128 v[38:41], v61 offset:34752
	s_waitcnt vmcnt(11)
	s_waitcnt lgkmcnt(6)
	v_mfma_f32_16x16x32_bf16 v[42:45], v[228:231], v[164:167], v[42:45]
	v_mfma_f32_16x16x32_bf16 v[46:49], v[232:235], v[164:167], v[46:49]
	ds_read_b128 v[228:231], v61 offset:1536
	ds_read_b128 v[232:235], v61 offset:34816
	s_waitcnt vmcnt(10)
	s_waitcnt lgkmcnt(6)
	v_mfma_f32_16x16x32_bf16 v[42:45], v[236:239], v[168:171], v[42:45]
	v_mfma_f32_16x16x32_bf16 v[46:49], v[240:243], v[168:171], v[46:49]
	ds_read_b128 v[236:239], v61 offset:1600
	ds_read_b128 v[240:243], v61 offset:34880
	s_waitcnt vmcnt(9)
	s_waitcnt lgkmcnt(6)
	v_mfma_f32_16x16x32_bf16 v[42:45], v[244:247], v[172:175], v[42:45]
	v_mfma_f32_16x16x32_bf16 v[46:49], v[248:251], v[172:175], v[46:49]
	ds_read_b128 v[244:247], v61 offset:1664
	ds_read_b128 v[248:251], v61 offset:34944
	s_waitcnt vmcnt(8)
	s_waitcnt lgkmcnt(6)
	v_mfma_f32_16x16x32_bf16 v[42:45], v[34:37], v[176:179], v[42:45]
	v_mfma_f32_16x16x32_bf16 v[46:49], v[38:41], v[176:179], v[46:49]
	ds_read_b128 v[34:37], v61 offset:1728
	ds_read_b128 v[38:41], v61 offset:35008
	s_waitcnt vmcnt(7)
	s_waitcnt lgkmcnt(6)
	v_mfma_f32_16x16x32_bf16 v[42:45], v[228:231], v[180:183], v[42:45]
	v_mfma_f32_16x16x32_bf16 v[46:49], v[232:235], v[180:183], v[46:49]
	ds_read_b128 v[228:231], v61 offset:1792
	ds_read_b128 v[232:235], v61 offset:35072
	s_waitcnt vmcnt(6)
	s_waitcnt lgkmcnt(6)
	v_mfma_f32_16x16x32_bf16 v[42:45], v[236:239], v[184:187], v[42:45]
	v_mfma_f32_16x16x32_bf16 v[46:49], v[240:243], v[184:187], v[46:49]
	ds_read_b128 v[236:239], v61 offset:1856
	ds_read_b128 v[240:243], v61 offset:35136
	s_waitcnt vmcnt(5)
	s_waitcnt lgkmcnt(6)
	v_mfma_f32_16x16x32_bf16 v[42:45], v[244:247], v[188:191], v[42:45]
	v_mfma_f32_16x16x32_bf16 v[46:49], v[248:251], v[188:191], v[46:49]
	ds_read_b128 v[244:247], v61 offset:1920
	ds_read_b128 v[248:251], v61 offset:35200
	s_waitcnt vmcnt(4)
	s_waitcnt lgkmcnt(6)
	v_mfma_f32_16x16x32_bf16 v[42:45], v[34:37], v[192:195], v[42:45]
	v_mfma_f32_16x16x32_bf16 v[46:49], v[38:41], v[192:195], v[46:49]
	ds_read_b128 v[34:37], v61 offset:1984
	ds_read_b128 v[38:41], v61 offset:35264
	s_waitcnt vmcnt(3)
	s_waitcnt lgkmcnt(6)
	v_mfma_f32_16x16x32_bf16 v[42:45], v[228:231], v[196:199], v[42:45]
	v_mfma_f32_16x16x32_bf16 v[46:49], v[232:235], v[196:199], v[46:49]
	s_waitcnt vmcnt(2)
	s_waitcnt lgkmcnt(4)
	v_mfma_f32_16x16x32_bf16 v[42:45], v[236:239], v[200:203], v[42:45]
	v_mfma_f32_16x16x32_bf16 v[46:49], v[240:243], v[200:203], v[46:49]
	s_waitcnt vmcnt(1)
	s_waitcnt lgkmcnt(2)
	v_mfma_f32_16x16x32_bf16 v[42:45], v[244:247], v[204:207], v[42:45]
	v_mfma_f32_16x16x32_bf16 v[46:49], v[248:251], v[204:207], v[46:49]
	s_waitcnt vmcnt(0)
	s_waitcnt lgkmcnt(0)
	v_mfma_f32_16x16x32_bf16 v[42:45], v[34:37], v[224:227], v[42:45]
	v_mfma_f32_16x16x32_bf16 v[46:49], v[38:41], v[224:227], v[46:49]
	s_nop 7
	s_nop 1
	v_cvt_pk_bf16_f32 v64, v42, v43
	v_cvt_pk_bf16_f32 v65, v44, v45
	v_cvt_pk_bf16_f32 v66, v46, v47
	v_cvt_pk_bf16_f32 v67, v48, v49
	global_store_dwordx4 v63, v[64:67], s[68:69]
.Llg32_done:
	s_load_dwordx4 s[76:79], s[0:1], 0x48
	v_readlane_b32 s2, v255, 45
	s_lshl_b32 s74, s2, 6
	s_mov_b32 s75, s55
	s_lshl_b64 s[6:7], s[74:75], 2
	v_readlane_b32 s3, v255, 46
	s_waitcnt lgkmcnt(0)
	s_add_u32 s2, s76, s6
	s_addc_u32 s3, s77, s7
	v_lshlrev_b32_e32 v1, 5, v10
	s_add_u32 s6, s78, s6
	v_and_b32_e32 v11, 63, v10
	v_and_b32_e32 v4, 0xe0, v1
	v_mov_b32_e32 v5, v0
	s_addc_u32 s7, s79, s7
	v_lshl_add_u64 v[2:3], s[6:7], 0, v[4:5]
	v_cmp_gt_u32_e64 s[38:39], 48, v11
	v_cmp_lt_u32_e64 s[40:41], 47, v11
	s_and_saveexec_b64 s[6:7], s[40:41]
	s_xor_b64 s[16:17], exec, s[6:7]
	s_cbranch_execz .LBB0_537
	global_load_dword v14, v[2:3], off
